# k18 + S4: the four gate (silu z) loads of the first l-tile issued together into dead VGPRs
# speedup vs baseline: 1.0031x; 1.0031x over previous
.LBB0_1545:
	v_add_u32_e32 v98, 0, v141
	ds_read_b128 v[98:101], v98
	ds_read_b128 v[102:105], v232
	v_xad_u32 v147, v141, 32, 0
	ds_read_b128 v[240:243], v147
	ds_read_b128 v[244:247], v233
	v_xad_u32 v147, v141, 64, 0
	v_add_u32_e32 v149, 0, v143
	s_waitcnt lgkmcnt(2)
	v_mfma_f32_32x32x16_bf16 v[98:113], v[98:101], v[102:105], 0
	v_add_u32_e32 v151, 0x20000, v149
	v_add_u32_e32 v143, 0x80, v143
	s_waitcnt lgkmcnt(0)
	v_mfma_f32_32x32x16_bf16 v[98:113], v[240:243], v[244:247], v[98:113]
	ds_read_b128 v[240:243], v147
	ds_read_b128 v[244:247], v234
	v_xor_b32_e32 v147, 0x60, v141
	v_add_u32_e32 v147, 0, v147
	s_waitcnt lgkmcnt(0)
	v_mfma_f32_32x32x16_bf16 v[98:113], v[240:243], v[244:247], v[98:113]
	ds_read_b128 v[240:243], v147
	ds_read_b128 v[244:247], v235
	v_xor_b32_e32 v147, 0x80, v141
	v_add_u32_e32 v147, 0, v147
	s_waitcnt lgkmcnt(0)
	v_mfma_f32_32x32x16_bf16 v[98:113], v[240:243], v[244:247], v[98:113]
	ds_read_b128 v[240:243], v147
	ds_read_b128 v[244:247], v236
	v_xor_b32_e32 v147, 0xa0, v141
	v_add_u32_e32 v147, 0, v147
	s_waitcnt lgkmcnt(0)
	v_mfma_f32_32x32x16_bf16 v[98:113], v[240:243], v[244:247], v[98:113]
	ds_read_b128 v[240:243], v147
	ds_read_b128 v[244:247], v237
	v_xor_b32_e32 v147, 0xc0, v141
	v_add_u32_e32 v147, 0, v147
	s_waitcnt lgkmcnt(0)
	v_mfma_f32_32x32x16_bf16 v[98:113], v[240:243], v[244:247], v[98:113]
	ds_read_b128 v[240:243], v147
	ds_read_b128 v[244:247], v238
	v_xor_b32_e32 v147, 0xe0, v141
	v_add_u32_e32 v147, 0, v147
	v_add_u32_e32 v141, 0x2000, v141
	s_waitcnt lgkmcnt(0)
	v_mfma_f32_32x32x16_bf16 v[98:113], v[240:243], v[244:247], v[98:113]
	ds_read_b128 v[240:243], v147
	ds_read_b128 v[244:247], v239
	v_add_u32_e32 v147, s2, v179
	v_cmp_le_u32_e32 vcc, v147, v185
	s_add_i32 s2, s2, 32
	s_add_i32 s0, s51, s2
	s_cmp_lg_u32 s0, 0
	s_waitcnt lgkmcnt(0)
	v_mfma_f32_32x32x16_bf16 v[98:113], v[240:243], v[244:247], v[98:113]
	ds_read_b128 v[240:243], v151
	v_add_u32_e32 v151, 0x20800, v149
	ds_read_b128 v[244:247], v151
	s_waitcnt lgkmcnt(1)
	v_sub_f32_e32 v151, v135, v240
	v_exp_f32_e32 v151, v151
	v_add_u32_e32 v240, 0x20820, v149
	s_nop 4
	v_mul_f32_e32 v98, v98, v151
	s_waitcnt lgkmcnt(0)
	v_mul_f32_e32 v98, v244, v98
	v_cndmask_b32_e32 v151, 0, v98, vcc
	v_sub_f32_e32 v98, v135, v241
	v_exp_f32_e32 v98, v98
	v_cmp_lt_u32_e32 vcc, v147, v185
	v_mul_f32_e32 v98, v99, v98
	v_mul_f32_e32 v98, v245, v98
	v_cndmask_b32_e32 v244, 0, v98, vcc
	v_sub_f32_e32 v98, v135, v242
	v_exp_f32_e32 v98, v98
	v_add_u32_e32 v99, 2, v147
	v_cmp_le_u32_e32 vcc, v99, v185
	v_add_u32_e32 v99, 3, v147
	v_mul_f32_e32 v98, v100, v98
	v_mul_f32_e32 v98, v246, v98
	v_cndmask_b32_e32 v245, 0, v98, vcc
	v_sub_f32_e32 v98, v135, v243
	v_exp_f32_e32 v98, v98
	v_cmp_le_u32_e32 vcc, v99, v185
	ds_read_b128 v[240:243], v240
	v_mul_f32_e32 v98, v101, v98
	v_mul_f32_e32 v98, v247, v98
	v_cndmask_b32_e32 v246, 0, v98, vcc
	v_add_u32_e32 v98, 0x20020, v149
	ds_read_b128 v[98:101], v98
	v_add_u32_e32 v247, 8, v147
	v_cmp_le_u32_e32 vcc, v247, v185
	v_add_u32_e32 v247, 16, v147
	s_waitcnt lgkmcnt(0)
	v_sub_f32_e32 v98, v135, v98
	v_exp_f32_e32 v98, v98
	s_nop 0
	v_mul_f32_e32 v98, v102, v98
	v_mul_f32_e32 v98, v240, v98
	v_cndmask_b32_e32 v240, 0, v98, vcc
	v_sub_f32_e32 v98, v135, v99
	v_exp_f32_e32 v98, v98
	v_add_u32_e32 v99, 9, v147
	v_cmp_le_u32_e32 vcc, v99, v185
	v_add_u32_e32 v99, 10, v147
	v_mul_f32_e32 v98, v103, v98
	v_mul_f32_e32 v98, v241, v98
	v_cndmask_b32_e32 v241, 0, v98, vcc
	v_sub_f32_e32 v98, v135, v100
	v_exp_f32_e32 v98, v98
	v_cmp_le_u32_e32 vcc, v99, v185
	v_add_u32_e32 v99, 11, v147
	v_add_u32_e32 v102, 0x20840, v149
	v_mul_f32_e32 v98, v104, v98
	v_mul_f32_e32 v98, v242, v98
	v_cndmask_b32_e32 v242, 0, v98, vcc
	v_sub_f32_e32 v98, v135, v101
	v_exp_f32_e32 v98, v98
	v_cmp_le_u32_e32 vcc, v99, v185
	v_mul_f32_e32 v98, v105, v98
	v_mul_f32_e32 v98, v243, v98
	v_cndmask_b32_e32 v243, 0, v98, vcc
	v_add_u32_e32 v98, 0x20040, v149
	ds_read_b128 v[98:101], v98
	ds_read_b128 v[102:105], v102
	v_cmp_le_u32_e32 vcc, v247, v185
	v_add_u32_e32 v247, 24, v147
	s_waitcnt lgkmcnt(1)
	v_sub_f32_e32 v98, v135, v98
	v_exp_f32_e32 v98, v98
	s_nop 0
	v_mul_f32_e32 v98, v106, v98
	s_waitcnt lgkmcnt(0)
	v_mul_f32_e32 v98, v102, v98
	v_cndmask_b32_e32 v106, 0, v98, vcc
	v_sub_f32_e32 v98, v135, v99
	v_exp_f32_e32 v98, v98
	v_add_u32_e32 v99, 17, v147
	v_cmp_le_u32_e32 vcc, v99, v185
	v_add_u32_e32 v99, 18, v147
	v_mul_f32_e32 v98, v107, v98
	v_mul_f32_e32 v98, v103, v98
	v_cndmask_b32_e32 v107, 0, v98, vcc
	v_sub_f32_e32 v98, v135, v100
	v_exp_f32_e32 v98, v98
	v_cmp_le_u32_e32 vcc, v99, v185
	v_add_u32_e32 v99, 19, v147
	v_add_u32_e32 v102, 0x20860, v149
	v_mul_f32_e32 v98, v108, v98
	v_mul_f32_e32 v98, v104, v98
	v_cndmask_b32_e32 v108, 0, v98, vcc
	v_sub_f32_e32 v98, v135, v101
	v_exp_f32_e32 v98, v98
	v_cmp_le_u32_e32 vcc, v99, v185
	v_mul_f32_e32 v98, v109, v98
	v_mul_f32_e32 v98, v105, v98
	v_cndmask_b32_e32 v109, 0, v98, vcc
	v_add_u32_e32 v98, 0x20060, v149
	ds_read_b128 v[98:101], v98
	ds_read_b128 v[102:105], v102
	v_cmp_le_u32_e32 vcc, v247, v185
	s_waitcnt lgkmcnt(1)
	v_sub_f32_e32 v98, v135, v98
	v_exp_f32_e32 v98, v98
	s_nop 0
	v_mul_f32_e32 v98, v110, v98
	s_waitcnt lgkmcnt(0)
	v_mul_f32_e32 v98, v102, v98
	v_cndmask_b32_e32 v110, 0, v98, vcc
	v_sub_f32_e32 v98, v135, v99
	v_exp_f32_e32 v98, v98
	v_add_u32_e32 v99, 25, v147
	v_cmp_le_u32_e32 vcc, v99, v185
	v_add_u32_e32 v99, 26, v147
	v_mul_f32_e32 v98, v111, v98
	v_mul_f32_e32 v98, v103, v98
	v_cndmask_b32_e32 v111, 0, v98, vcc
	v_sub_f32_e32 v98, v135, v100
	v_exp_f32_e32 v98, v98
	v_cmp_le_u32_e32 vcc, v99, v185
	v_add_u32_e32 v99, 27, v147
	v_cvt_pk_bf16_f32 v102, v151, v244
	v_mul_f32_e32 v98, v112, v98
	v_mul_f32_e32 v98, v104, v98
	v_cndmask_b32_e32 v112, 0, v98, vcc
	v_sub_f32_e32 v98, v135, v101
	v_exp_f32_e32 v98, v98
	v_cmp_le_u32_e32 vcc, v99, v185
	v_cvt_pk_bf16_f32 v103, v245, v246
	v_cvt_pk_bf16_f32 v104, v240, v241
	v_mul_f32_e32 v98, v113, v98
	v_mul_f32_e32 v98, v105, v98
	v_cndmask_b32_e32 v101, 0, v98, vcc
	v_cvt_pk_bf16_f32 v105, v242, v243
	v_cvt_pk_bf16_f32 v98, v106, v107
	v_add_u32_e32 v106, 0, v145
	v_cvt_pk_bf16_f32 v99, v108, v109
	v_cvt_pk_bf16_f32 v100, v110, v111
	v_cvt_pk_bf16_f32 v101, v112, v101
	ds_read_b64_tr_b16 v[108:109], v106
	ds_read_b64_tr_b16 v[110:111], v106 offset:512
	s_waitcnt lgkmcnt(0)
	v_mfma_f32_32x32x16_bf16 v[50:65], v[108:111], v[102:105], v[50:65]
	ds_read_b64_tr_b16 v[108:109], v106 offset:1024
	ds_read_b64_tr_b16 v[110:111], v106 offset:1536
	v_add_u32_e32 v145, 0x800, v145
	s_waitcnt lgkmcnt(0)
	v_mfma_f32_32x32x16_bf16 v[50:65], v[108:111], v[98:101], v[50:65]
	ds_read_b64_tr_b16 v[108:109], v106 offset:8192
	ds_read_b64_tr_b16 v[110:111], v106 offset:8704
	s_waitcnt lgkmcnt(0)
	v_mfma_f32_32x32x16_bf16 v[34:49], v[108:111], v[102:105], v[34:49]
	ds_read_b64_tr_b16 v[102:103], v106 offset:9216
	ds_read_b64_tr_b16 v[104:105], v106 offset:9728
	s_waitcnt lgkmcnt(0)
	v_mfma_f32_32x32x16_bf16 v[34:49], v[102:105], v[98:101], v[34:49]
	s_cbranch_scc1 .LBB0_1545
	v_exp_f32_e32 v112, v137
	v_lshlrev_b32_e32 v147, 16, v118
	v_and_b32_e32 v149, 0xffff0000, v118
	v_lshlrev_b32_e32 v246, 16, v114
	v_and_b32_e32 v247, 0xffff0000, v114
	v_lshlrev_b32_e32 v248, 16, v115
	v_and_b32_e32 v249, 0xffff0000, v115
	v_lshlrev_b32_e32 v250, 16, v116
	v_and_b32_e32 v251, 0xffff0000, v116
	v_lshlrev_b32_e32 v252, 16, v117
	v_and_b32_e32 v253, 0xffff0000, v117
	v_fma_f32 v118, v112, v82, v18
	v_fma_f32 v117, v112, v83, v19
	v_fma_f32 v116, v112, v84, v20
	v_fma_f32 v115, v112, v85, v21
	v_fma_f32 v114, v112, v86, v22
	v_fma_f32 v113, v112, v87, v23
	v_fma_f32 v111, v112, v88, v24
	v_fma_f32 v24, v112, v94, v30
	v_fma_f32 v23, v112, v95, v31
	v_fma_f32 v22, v112, v96, v32
	v_fma_f32 v106, v112, v66, v2
	v_fma_f32 v105, v112, v67, v3
	v_fma_f32 v104, v112, v68, v4
	v_fma_f32 v103, v112, v69, v5
	v_fma_f32 v102, v112, v70, v6
	v_fma_f32 v101, v112, v71, v7
	v_fma_f32 v100, v112, v72, v8
	v_fma_f32 v99, v112, v73, v9
	v_fma_f32 v98, v112, v74, v10
	v_fma_f32 v32, v112, v75, v11
	v_fma_f32 v31, v112, v76, v12
	v_fma_f32 v30, v112, v77, v13
	global_load_dwordx4 v[2:5], v[156:157], off
	global_load_dwordx4 v[6:9], v[156:157], off offset:1024
	global_load_dwordx4 v[10:13], v[156:157], off offset:2048
	global_load_dwordx4 v[18:21], v[156:157], off offset:3072
	ds_read_b128 v[66:69], v232
	v_lshlrev_b32_e32 v240, 16, v120
	v_and_b32_e32 v120, 0xffff0000, v120
	v_lshlrev_b32_e32 v241, 16, v121
	v_and_b32_e32 v121, 0xffff0000, v121
	v_lshlrev_b32_e32 v242, 16, v122
	v_and_b32_e32 v122, 0xffff0000, v122
	v_lshlrev_b32_e32 v243, 16, v123
	v_and_b32_e32 v123, 0xffff0000, v123
	v_fmac_f32_e32 v33, v112, v97
	v_fma_f32 v110, v112, v89, v25
	v_fma_f32 v109, v112, v90, v26
	v_fma_f32 v108, v112, v91, v27
	v_fma_f32 v107, v112, v92, v28
	v_fma_f32 v25, v112, v93, v29
	v_fmac_f32_e32 v23, v139, v120
	v_fmac_f32_e32 v33, v139, v121
	v_fmac_f32_e32 v105, v139, v122
	v_fmac_f32_e32 v103, v139, v123
	ds_read_b128 v[120:123], v233
	v_lshlrev_b32_e32 v137, 16, v126
	v_and_b32_e32 v126, 0xffff0000, v126
	v_lshlrev_b32_e32 v141, 16, v127
	v_and_b32_e32 v127, 0xffff0000, v127
	v_lshlrev_b32_e32 v244, 16, v124
	v_and_b32_e32 v124, 0xffff0000, v124
	v_lshlrev_b32_e32 v245, 16, v125
	v_and_b32_e32 v125, 0xffff0000, v125
	v_fmac_f32_e32 v117, v139, v126
	v_fmac_f32_e32 v115, v139, v127
	v_fmac_f32_e32 v101, v139, v124
	v_fmac_f32_e32 v99, v139, v125
	ds_read_b128 v[124:127], v234
	v_fmac_f32_e32 v24, v139, v240
	v_fmac_f32_e32 v22, v139, v241
	v_fmac_f32_e32 v106, v139, v242
	v_fmac_f32_e32 v104, v139, v243
	ds_read_b128 v[240:243], v235
	v_fma_f32 v29, v112, v78, v14
	v_fma_f32 v28, v112, v79, v15
	v_fma_f32 v16, v112, v80, v16
	v_fmac_f32_e32 v17, v112, v81
	v_and_b32_e32 v27, 64, v214
	v_xor_b32_e32 v26, 32, v214
	v_add_u32_e32 v27, 64, v27
	v_cmp_lt_i32_e32 vcc, v26, v27
	s_lshl_b32 s12, s54, 9
	s_waitcnt vmcnt(3) lgkmcnt(3)
	v_mfma_f32_32x32x16_bf16 v[82:97], v[2:5], v[66:69], 0
	v_cndmask_b32_e32 v26, v214, v26, vcc
	v_lshlrev_b32_e32 v112, 2, v26
	v_or_b32_e32 v26, s20, v183
	v_ashrrev_i32_e32 v27, 31, v26
	v_lshl_add_u64 v[14:15], v[132:133], 0, s[12:13]
	v_lshlrev_b64 v[26:27], 12, v[26:27]
	v_lshl_add_u64 v[26:27], v[14:15], 0, v[26:27]
	s_waitcnt vmcnt(2) lgkmcnt(2)
	v_mfma_f32_32x32x16_bf16 v[82:97], v[6:9], v[120:123], v[82:97]
	v_lshlrev_b32_e32 v143, 16, v128
	v_and_b32_e32 v128, 0xffff0000, v128
	v_lshlrev_b32_e32 v145, 16, v129
	v_and_b32_e32 v129, 0xffff0000, v129
	v_lshlrev_b32_e32 v151, 16, v119
	v_and_b32_e32 v119, 0xffff0000, v119
	v_fmac_f32_e32 v118, v139, v137
	s_waitcnt vmcnt(1) lgkmcnt(1)
	v_mfma_f32_32x32x16_bf16 v[82:97], v[10:13], v[124:127], v[82:97]
	v_fmac_f32_e32 v116, v139, v141
	v_fmac_f32_e32 v114, v139, v143
	v_fmac_f32_e32 v113, v139, v128
	v_fmac_f32_e32 v111, v139, v145
	v_fmac_f32_e32 v110, v139, v129
	v_fmac_f32_e32 v109, v139, v147
	v_fmac_f32_e32 v108, v139, v149
	s_waitcnt vmcnt(0) lgkmcnt(0)
	v_mfma_f32_32x32x16_bf16 v[82:97], v[18:21], v[240:243], v[82:97]
	global_load_dwordx4 v[6:9], v[170:171], off
	global_load_dwordx4 v[10:13], v[172:173], off
	global_load_dwordx4 v[18:21], v[174:175], off
	global_load_dwordx4 v[70:73], v[176:177], off
	ds_read_b128 v[2:5], v236
	v_fmac_f32_e32 v107, v139, v151
	v_fmac_f32_e32 v25, v139, v119
	v_fmac_f32_e32 v102, v139, v244
	v_fmac_f32_e32 v100, v139, v245
	v_fmac_f32_e32 v98, v139, v246
	v_fmac_f32_e32 v32, v139, v247
	v_fmac_f32_e32 v31, v139, v248
	v_fmac_f32_e32 v30, v139, v249
	v_fmac_f32_e32 v29, v139, v250
	v_fmac_f32_e32 v28, v139, v251
	v_fmac_f32_e32 v16, v139, v252
	v_fmac_f32_e32 v17, v139, v253
	s_waitcnt vmcnt(3) lgkmcnt(0)
	v_mfma_f32_32x32x16_bf16 v[82:97], v[6:9], v[2:5], v[82:97]
	ds_read_b128 v[6:9], v237
	s_waitcnt vmcnt(2) lgkmcnt(0)
	v_mfma_f32_32x32x16_bf16 v[82:97], v[10:13], v[6:9], v[82:97]
	ds_read_b128 v[10:13], v238
	s_waitcnt vmcnt(1) lgkmcnt(0)
	v_mfma_f32_32x32x16_bf16 v[82:97], v[18:21], v[10:13], v[82:97]
	ds_read_b128 v[18:21], v239
	s_waitcnt vmcnt(0) lgkmcnt(0)
	v_mfma_f32_32x32x16_bf16 v[82:97], v[70:73], v[18:21], v[82:97]
	global_load_dwordx4 v[70:73], v[166:167], off
	s_nop 0
	global_load_dwordx4 v[166:169], v[168:169], off
	s_nop 0
	global_load_dwordx4 v[170:173], v[164:165], off
	s_nop 0
	global_load_dwordx4 v[162:165], v[162:163], off
	s_waitcnt vmcnt(3)
	v_mfma_f32_32x32x16_bf16 v[66:81], v[70:73], v[66:69], 0
	s_waitcnt vmcnt(2)
	v_mfma_f32_32x32x16_bf16 v[66:81], v[166:169], v[120:123], v[66:81]
	s_waitcnt vmcnt(1)
	v_mfma_f32_32x32x16_bf16 v[66:81], v[170:173], v[124:127], v[66:81]
	global_load_dwordx4 v[120:123], v[160:161], off
	global_load_dwordx4 v[124:127], v[158:159], off
	s_nop 0
	global_load_dwordx4 v[156:159], v[152:153], off
	s_nop 0
	global_load_dwordx4 v[152:155], v[154:155], off
	s_waitcnt vmcnt(4)
	v_mfma_f32_32x32x16_bf16 v[66:81], v[162:165], v[240:243], v[66:81]
	s_waitcnt vmcnt(3)
	v_mfma_f32_32x32x16_bf16 v[66:81], v[120:123], v[2:5], v[66:81]
	v_add_u32_e32 v2, 0x2000, v213
	global_load_dword v123, v131, s[22:23]
	s_waitcnt vmcnt(3)
	v_mfma_f32_32x32x16_bf16 v[66:81], v[124:127], v[6:9], v[66:81]
	s_waitcnt vmcnt(2)
	v_mfma_f32_32x32x16_bf16 v[66:81], v[156:159], v[10:13], v[66:81]
	s_waitcnt vmcnt(1)
	v_mfma_f32_32x32x16_bf16 v[66:81], v[152:155], v[18:21], v[66:81]
	ds_read2_b64 v[18:21], v213 offset1:2
	ds_read2_b64 v[10:13], v213 offset0:4 offset1:6
	ds_read2_b64 v[6:9], v2 offset1:2
	ds_read2_b64 v[2:5], v2 offset0:4 offset1:6
	global_load_dwordx4 v[152:155], v[26:27], off
	global_load_dwordx4 v[156:159], v[26:27], off offset:32
	global_load_dwordx4 v[160:163], v[26:27], off offset:64
	global_load_dwordx4 v[164:167], v[26:27], off offset:96
	s_waitcnt vmcnt(0)
	v_mov_b32_e32 v124, v152
	v_mov_b32_e32 v125, v153
	v_mov_b32_e32 v126, v154
	v_mov_b32_e32 v127, v155
	v_mov_b32_e32 v137, v126
	v_mov_b32_e32 v139, v127
	v_mov_b32_e32 v126, v156
	v_mov_b32_e32 v127, v157
	v_mov_b32_e32 v128, v158
	v_mov_b32_e32 v129, v159
	v_permlane32_swap_b32_e32 v124, v137
	v_lshlrev_b32_e32 v119, 16, v124
	v_permlane32_swap_b32_e32 v125, v139
	v_mul_f32_e32 v122, v118, v119
	v_and_b32_e32 v118, 0xffff0000, v124
	v_mul_f32_e32 v121, v117, v118
	v_lshlrev_b32_e32 v117, 16, v125
	v_mul_f32_e32 v120, v116, v117
	v_and_b32_e32 v116, 0xffff0000, v125
	v_mul_f32_e32 v119, v115, v116
	v_mul_f32_e32 v115, v121, v121
	v_mul_f32_e32 v116, v119, v119
	v_fmac_f32_e32 v115, v122, v122
	v_fmac_f32_e32 v116, v120, v120
	v_add_f32_e32 v115, v115, v116
	v_lshlrev_b32_e32 v116, 16, v137
	v_mul_f32_e32 v117, v114, v116
	v_and_b32_e32 v114, 0xffff0000, v137
	v_mul_f32_e32 v118, v113, v114
	v_lshlrev_b32_e32 v113, 16, v139
	v_mul_f32_e32 v113, v111, v113
	v_and_b32_e32 v111, 0xffff0000, v139
	v_mul_f32_e32 v114, v110, v111
	v_mul_f32_e32 v110, v118, v118
	v_mul_f32_e32 v111, v114, v114
	v_fmac_f32_e32 v110, v117, v117
	v_fmac_f32_e32 v111, v113, v113
	v_add_f32_e32 v110, v110, v111
	v_add_f32_e32 v110, v115, v110
	s_waitcnt vmcnt(0)
	v_permlane32_swap_b32_e32 v126, v128
	v_lshlrev_b32_e32 v111, 16, v126
	v_permlane32_swap_b32_e32 v127, v129
	v_mul_f32_e32 v115, v109, v111
	v_and_b32_e32 v109, 0xffff0000, v126
	v_mul_f32_e32 v116, v108, v109
	v_lshlrev_b32_e32 v108, 16, v127
	v_mul_f32_e32 v108, v107, v108
	v_and_b32_e32 v107, 0xffff0000, v127
	v_mul_f32_e32 v109, v25, v107
	v_mul_f32_e32 v25, v116, v116
	v_mul_f32_e32 v107, v109, v109
	v_fmac_f32_e32 v25, v115, v115
	v_fmac_f32_e32 v107, v108, v108
	v_add_f32_e32 v25, v25, v107
	v_lshlrev_b32_e32 v107, 16, v128
	v_add_f32_e32 v25, v110, v25
	v_mul_f32_e32 v110, v24, v107
	v_and_b32_e32 v24, 0xffff0000, v128
	v_mul_f32_e32 v111, v23, v24
	v_lshlrev_b32_e32 v23, 16, v129
	v_mul_f32_e32 v107, v22, v23
	v_and_b32_e32 v22, 0xffff0000, v129
	v_mul_f32_e32 v33, v33, v22
	v_mul_f32_e32 v22, v111, v111
	v_mul_f32_e32 v23, v33, v33
	v_fmac_f32_e32 v22, v110, v110
	v_fmac_f32_e32 v23, v107, v107
	v_add_f32_e32 v22, v22, v23
	v_add_f32_e32 v124, v22, v25
	v_mov_b32_e32 v22, v160
	v_mov_b32_e32 v23, v161
	v_mov_b32_e32 v24, v162
	v_mov_b32_e32 v25, v163
	s_waitcnt vmcnt(0)
	v_mov_b32_e32 v125, v24
	v_mov_b32_e32 v126, v25
	v_mov_b32_e32 v24, v164
	v_mov_b32_e32 v25, v165
	v_mov_b32_e32 v26, v166
	v_mov_b32_e32 v27, v167
	v_permlane32_swap_b32_e32 v22, v125
	v_permlane32_swap_b32_e32 v23, v126
	s_waitcnt vmcnt(0)
	v_mov_b32_e32 v127, v26
	v_lshlrev_b32_e32 v26, 16, v22
	v_and_b32_e32 v22, 0xffff0000, v22
	v_mov_b32_e32 v128, v27
	v_mul_f32_e32 v27, v105, v22
	v_lshlrev_b32_e32 v22, 16, v23
	v_and_b32_e32 v23, 0xffff0000, v23
	v_mul_f32_e32 v23, v103, v23
	v_mul_f32_e32 v26, v106, v26
	v_mul_f32_e32 v22, v104, v22
	v_mul_f32_e32 v103, v27, v27
	v_mul_f32_e32 v104, v23, v23
	v_fmac_f32_e32 v103, v26, v26
	v_fmac_f32_e32 v104, v22, v22
	v_add_f32_e32 v103, v103, v104
	v_lshlrev_b32_e32 v104, 16, v125
	v_mul_f32_e32 v102, v102, v104
	v_and_b32_e32 v104, 0xffff0000, v125
	v_mul_f32_e32 v101, v101, v104
	v_lshlrev_b32_e32 v104, 16, v126
	v_mul_f32_e32 v100, v100, v104
	v_and_b32_e32 v104, 0xffff0000, v126
	v_mul_f32_e32 v99, v99, v104
	v_mul_f32_e32 v104, v101, v101
	v_mul_f32_e32 v105, v99, v99
	v_fmac_f32_e32 v104, v102, v102
	v_fmac_f32_e32 v105, v100, v100
	v_permlane32_swap_b32_e32 v24, v127
	v_add_f32_e32 v103, v124, v103
	v_add_f32_e32 v104, v104, v105
	v_permlane32_swap_b32_e32 v25, v128
	v_add_f32_e32 v103, v104, v103
	v_lshlrev_b32_e32 v104, 16, v24
	v_and_b32_e32 v24, 0xffff0000, v24
	v_mul_f32_e32 v32, v32, v24
	v_lshlrev_b32_e32 v24, 16, v25
	v_and_b32_e32 v25, 0xffff0000, v25
	v_mul_f32_e32 v25, v30, v25
	v_mul_f32_e32 v98, v98, v104
	v_mul_f32_e32 v24, v31, v24
	v_mul_f32_e32 v30, v32, v32
	v_mul_f32_e32 v31, v25, v25
	v_fmac_f32_e32 v30, v98, v98
	v_fmac_f32_e32 v31, v24, v24
	v_add_f32_e32 v30, v30, v31
	v_lshlrev_b32_e32 v31, 16, v127
	v_mul_f32_e32 v29, v29, v31
	v_and_b32_e32 v31, 0xffff0000, v127
	v_mul_f32_e32 v28, v28, v31
	v_lshlrev_b32_e32 v31, 16, v128
	v_mul_f32_e32 v16, v16, v31
	v_and_b32_e32 v31, 0xffff0000, v128
	v_mul_f32_e32 v17, v17, v31
	v_add_f32_e32 v30, v103, v30
	v_mul_f32_e32 v31, v28, v28
	v_mul_f32_e32 v103, v17, v17
	v_fmac_f32_e32 v31, v29, v29
	v_fmac_f32_e32 v103, v16, v16
	v_add_f32_e32 v31, v31, v103
	v_add_f32_e32 v30, v31, v30
	ds_bpermute_b32 v31, v112, v30
	s_and_saveexec_b64 s[2:3], s[4:5]
	s_cbranch_execz .LBB0_1548
	s_waitcnt lgkmcnt(0)
	v_add_f32_e32 v30, v30, v31
	ds_write_b32 v187, v30
